# stack1 + teams staggered at P5 start (4 groups by blockIdx bits 3-4, 0..10us) to de-phase the P5-P8 team chains
# speedup vs baseline: 1.0051x; 1.0038x over previous
;     __host__ __device__ void init(int M_, int G_, int c_) { so.init(M_, 1024, G_, c_); }
;     __host__ __device__ void init(int M_, int G_, int c_) { so.init(M_, 3072, G_, c_); }
;     __host__ __device__ void init(int M_, int start_, int stride_, int limit_) { so.init(M_, 3072, stride_, start_); start = start_; stride = stride_; limit = limit_; }
; __device__ __forceinline__ unsigned long long rt() { return __builtin_amdgcn_s_memrealtime(); }
; __global__ void __launch_bounds__(NWAVES * 64, 2) fwd(Args args) {
;     ...
;     if (IN(5)) {
;         const unsigned long long amp_t0_5 = (PROBE_AMP == 5) ? rt() : 0ull;
;         _Pragma("unroll 1") for (int rep_ = 0; rep_ < ((PROBE == 5) ? 2 : 1); ++rep_) {
;         pg8::Gemm g{OAB, WBAB_T, M, D, 512, D, D, 1}; pg8::MergeOrder S; S.init(M, G, (int)blockIdx.x);
;         pg8::EpiMerge E{GAB, MRG};
;         pg8::gemm_phase<pg8::EpiMerge, pg8::MergeOrder, true, true>(lds + RING_OFF, g, S, E);
.LBB0_946:
	s_bfe_u32 s98, s2, 0x20003
	s_cmp_eq_u32 s98, 0
	s_cbranch_scc1 .Lstag_done
.Lstag_loop:
	s_sleep 127
	s_sub_u32 s98, s98, 1
	s_cmp_lg_u32 s98, 0
	s_cbranch_scc1 .Lstag_loop

; #define LAS __attribute__((address_space(3)))
; __global__ void __launch_bounds__(NWAVES * 64, 2) fwd(Args args) {
;     extern __shared__ __attribute__((aligned(16))) unsigned char lds_raw[];
;     LAS unsigned char* lds = (LAS unsigned char*)lds_raw;
;     volatile LAS unsigned* MISC = (volatile LAS unsigned*)(lds + MISC_OFF);
;     const int tid = threadIdx.x, lane = tid & 63, wave = __builtin_amdgcn_readfirstlane(tid >> 6);
	.amdhsa_kernel _Z3fwd4Args
		.amdhsa_group_segment_fixed_size 0
		.amdhsa_private_segment_fixed_size 0
		.amdhsa_kernarg_size 424
		.amdhsa_user_sgpr_count 2
		.amdhsa_user_sgpr_dispatch_ptr 0
		.amdhsa_user_sgpr_queue_ptr 0
		.amdhsa_user_sgpr_kernarg_segment_ptr 1
		.amdhsa_user_sgpr_dispatch_id 0
		.amdhsa_user_sgpr_kernarg_preload_length 0
		.amdhsa_user_sgpr_kernarg_preload_offset 0
		.amdhsa_user_sgpr_private_segment_size 0
		.amdhsa_uses_dynamic_stack 0
		.amdhsa_enable_private_segment 0
		.amdhsa_system_sgpr_workgroup_id_x 1
		.amdhsa_system_sgpr_workgroup_id_y 0
		.amdhsa_system_sgpr_workgroup_id_z 0
		.amdhsa_system_sgpr_workgroup_info 0
		.amdhsa_system_vgpr_workitem_id 0
		.amdhsa_next_free_vgpr 248
		.amdhsa_next_free_sgpr 100
		.amdhsa_accum_offset 244
		.amdhsa_reserve_vcc 1
		.amdhsa_float_round_mode_32 0
		.amdhsa_float_round_mode_16_64 0
		.amdhsa_float_denorm_mode_32 3
		.amdhsa_float_denorm_mode_16_64 3
		.amdhsa_dx10_clamp 1
		.amdhsa_ieee_mode 1
		.amdhsa_fp16_overflow 0
		.amdhsa_tg_split 0
		.amdhsa_exception_fp_ieee_invalid_op 0
		.amdhsa_exception_fp_denorm_src 0
		.amdhsa_exception_fp_ieee_div_zero 0
		.amdhsa_exception_fp_ieee_overflow 0
		.amdhsa_exception_fp_ieee_underflow 0
		.amdhsa_exception_fp_ieee_inexact 0
		.amdhsa_exception_int_div_zero 0
	.end_amdhsa_kernel

; #define LAS __attribute__((address_space(3)))
; __global__ void __launch_bounds__(NWAVES * 64, 2) fwd(Args args) {
;     extern __shared__ __attribute__((aligned(16))) unsigned char lds_raw[];
;     LAS unsigned char* lds = (LAS unsigned char*)lds_raw;
;     volatile LAS unsigned* MISC = (volatile LAS unsigned*)(lds + MISC_OFF);
;     const int tid = threadIdx.x, lane = tid & 63, wave = __builtin_amdgcn_readfirstlane(tid >> 6);
amdhsa.kernels:
  - .agpr_count:     0
    .args:
      - .offset:         0
        .size:           168
        .value_kind:     by_value
      - .offset:         168
        .size:           4
        .value_kind:     hidden_block_count_x
      - .offset:         172
        .size:           4
        .value_kind:     hidden_block_count_y
      - .offset:         176
        .size:           4
        .value_kind:     hidden_block_count_z
      - .offset:         180
        .size:           2
        .value_kind:     hidden_group_size_x
      - .offset:         182
        .size:           2
        .value_kind:     hidden_group_size_y
      - .offset:         184
        .size:           2
        .value_kind:     hidden_group_size_z
      - .offset:         186
        .size:           2
        .value_kind:     hidden_remainder_x
      - .offset:         188
        .size:           2
        .value_kind:     hidden_remainder_y
      - .offset:         190
        .size:           2
        .value_kind:     hidden_remainder_z
      - .offset:         208
        .size:           8
        .value_kind:     hidden_global_offset_x
      - .offset:         216
        .size:           8
        .value_kind:     hidden_global_offset_y
      - .offset:         224
        .size:           8
        .value_kind:     hidden_global_offset_z
      - .offset:         232
        .size:           2
        .value_kind:     hidden_grid_dims
      - .offset:         288
        .size:           4
        .value_kind:     hidden_dynamic_lds_size
    .group_segment_fixed_size: 0
    .kernarg_segment_align: 8
    .kernarg_segment_size: 424
    .language:       OpenCL C
    .language_version:
      - 2
      - 0
    .max_flat_workgroup_size: 512
    .name:           _Z3fwd4Args
    .private_segment_fixed_size: 0
    .sgpr_count:     106
    .sgpr_spill_count: 37
    .symbol:         _Z3fwd4Args.kd
    .uniform_work_group_size: 1
    .uses_dynamic_stack: false
    .vgpr_count:     248
    .vgpr_spill_count: 0
    .wavefront_size: 64
